# P6 epilogue: second column half of x issued row by row as the first-half registers free up (one round trip instead of eight dependent ones)
# speedup vs baseline: 1.0083x; 1.0083x over previous
.LBB0_719:
	s_or_b64 exec, exec, s[52:53]
	v_lshlrev_b64 v[204:205], 2, v[200:201]
	s_waitcnt lgkmcnt(0)
	s_barrier
	v_lshl_add_u64 v[206:207], s[20:21], 0, v[204:205]
	global_load_dwordx4 v[196:199], v[206:207], off
	global_load_dwordx4 v[192:195], v[206:207], off offset:16
	global_load_dwordx4 v[226:229], v[206:207], off offset:512
	global_load_dwordx4 v[230:233], v[206:207], off offset:528
	v_add_u32_e32 v236, s27, v210
	v_lshlrev_b32_e32 v236, 12, v236
	v_add_u32_e32 v236, v236, v204
	v_lshl_add_u32 v209, v210, 2, 0
	ds_read_b32 v214, v209 offset:8192
	s_waitcnt lgkmcnt(0)
	v_pk_mul_f32 v[116:117], v[116:117], v[214:215] op_sel_hi:[1,0]
	v_pk_mul_f32 v[118:119], v[118:119], v[214:215] op_sel_hi:[1,0]
	v_pk_mul_f32 v[216:217], v[112:113], v[214:215] op_sel_hi:[1,0]
	v_pk_mul_f32 v[214:215], v[114:115], v[214:215] op_sel_hi:[1,0]
	s_waitcnt vmcnt(2)
	v_pk_fma_f32 v[114:115], v[198:199], v[118:119], v[190:191]
	v_pk_fma_f32 v[112:113], v[196:197], v[116:117], v[188:189]
	v_pk_fma_f32 v[118:119], v[194:195], v[214:215], v[186:187]
	v_pk_fma_f32 v[116:117], v[192:193], v[216:217], v[184:185]
	global_load_dwordx4 v[184:187], v236, s[48:49] offset:512
	global_load_dwordx4 v[188:191], v236, s[48:49] offset:528
	ds_read_b32 v234, v209 offset:8256
	s_waitcnt lgkmcnt(0)
	v_pk_mul_f32 v[124:125], v[124:125], v[234:235] op_sel_hi:[1,0]
	v_pk_mul_f32 v[126:127], v[126:127], v[234:235] op_sel_hi:[1,0]
	v_pk_mul_f32 v[238:239], v[120:121], v[234:235] op_sel_hi:[1,0]
	v_pk_mul_f32 v[234:235], v[122:123], v[234:235] op_sel_hi:[1,0]
	v_pk_fma_f32 v[122:123], v[198:199], v[126:127], v[182:183]
	v_pk_fma_f32 v[120:121], v[196:197], v[124:125], v[180:181]
	v_pk_fma_f32 v[126:127], v[194:195], v[234:235], v[178:179]
	v_pk_fma_f32 v[124:125], v[192:193], v[238:239], v[176:177]
	v_add_u32_e32 v237, 0x10000, v236
	global_load_dwordx4 v[176:179], v237, s[48:49] offset:512
	global_load_dwordx4 v[180:183], v237, s[48:49] offset:528
	ds_read_b32 v234, v209 offset:8320
	s_waitcnt lgkmcnt(0)
	v_pk_mul_f32 v[108:109], v[108:109], v[234:235] op_sel_hi:[1,0]
	v_pk_mul_f32 v[110:111], v[110:111], v[234:235] op_sel_hi:[1,0]
	v_pk_mul_f32 v[238:239], v[104:105], v[234:235] op_sel_hi:[1,0]
	v_pk_mul_f32 v[234:235], v[106:107], v[234:235] op_sel_hi:[1,0]
	v_pk_fma_f32 v[106:107], v[198:199], v[110:111], v[174:175]
	v_pk_fma_f32 v[104:105], v[196:197], v[108:109], v[172:173]
	v_pk_fma_f32 v[110:111], v[194:195], v[234:235], v[170:171]
	v_pk_fma_f32 v[108:109], v[192:193], v[238:239], v[168:169]
	v_add_u32_e32 v237, 0x20000, v236
	global_load_dwordx4 v[168:171], v237, s[48:49] offset:512
	global_load_dwordx4 v[172:175], v237, s[48:49] offset:528
	ds_read_b32 v234, v209 offset:8384
	s_waitcnt lgkmcnt(0)
	v_pk_mul_f32 v[100:101], v[100:101], v[234:235] op_sel_hi:[1,0]
	v_pk_mul_f32 v[102:103], v[102:103], v[234:235] op_sel_hi:[1,0]
	v_pk_mul_f32 v[96:97], v[96:97], v[234:235] op_sel_hi:[1,0]
	v_pk_mul_f32 v[98:99], v[98:99], v[234:235] op_sel_hi:[1,0]
	v_pk_fma_f32 v[102:103], v[198:199], v[102:103], v[166:167]
	v_pk_fma_f32 v[100:101], v[196:197], v[100:101], v[164:165]
	v_pk_fma_f32 v[98:99], v[194:195], v[98:99], v[162:163]
	v_pk_fma_f32 v[96:97], v[192:193], v[96:97], v[160:161]
	v_add_u32_e32 v237, 0x30000, v236
	global_load_dwordx4 v[160:163], v237, s[48:49] offset:512
	global_load_dwordx4 v[164:167], v237, s[48:49] offset:528
	ds_read_b32 v234, v209 offset:8704
	s_waitcnt lgkmcnt(0)
	v_pk_mul_f32 v[92:93], v[92:93], v[234:235] op_sel_hi:[1,0]
	v_pk_mul_f32 v[94:95], v[94:95], v[234:235] op_sel_hi:[1,0]
	v_pk_mul_f32 v[88:89], v[88:89], v[234:235] op_sel_hi:[1,0]
	v_pk_mul_f32 v[90:91], v[90:91], v[234:235] op_sel_hi:[1,0]
	v_pk_fma_f32 v[94:95], v[198:199], v[94:95], v[158:159]
	v_pk_fma_f32 v[92:93], v[196:197], v[92:93], v[156:157]
	v_pk_fma_f32 v[90:91], v[194:195], v[90:91], v[154:155]
	v_pk_fma_f32 v[88:89], v[192:193], v[88:89], v[152:153]
	v_add_u32_e32 v237, 0x80000, v236
	global_load_dwordx4 v[152:155], v237, s[48:49] offset:512
	global_load_dwordx4 v[156:159], v237, s[48:49] offset:528
	ds_read_b32 v234, v209 offset:8768
	s_waitcnt lgkmcnt(0)
	v_pk_mul_f32 v[84:85], v[84:85], v[234:235] op_sel_hi:[1,0]
	v_pk_mul_f32 v[86:87], v[86:87], v[234:235] op_sel_hi:[1,0]
	v_pk_mul_f32 v[80:81], v[80:81], v[234:235] op_sel_hi:[1,0]
	v_pk_mul_f32 v[82:83], v[82:83], v[234:235] op_sel_hi:[1,0]
	v_pk_fma_f32 v[86:87], v[198:199], v[86:87], v[150:151]
	v_pk_fma_f32 v[84:85], v[196:197], v[84:85], v[148:149]
	v_pk_fma_f32 v[82:83], v[194:195], v[82:83], v[146:147]
	v_pk_fma_f32 v[80:81], v[192:193], v[80:81], v[144:145]
	v_add_u32_e32 v237, 0x90000, v236
	global_load_dwordx4 v[144:147], v237, s[48:49] offset:512
	global_load_dwordx4 v[148:151], v237, s[48:49] offset:528
	ds_read_b32 v234, v209 offset:8832
	s_waitcnt lgkmcnt(0)
	v_pk_mul_f32 v[76:77], v[76:77], v[234:235] op_sel_hi:[1,0]
	v_pk_mul_f32 v[78:79], v[78:79], v[234:235] op_sel_hi:[1,0]
	v_pk_mul_f32 v[72:73], v[72:73], v[234:235] op_sel_hi:[1,0]
	v_pk_mul_f32 v[74:75], v[74:75], v[234:235] op_sel_hi:[1,0]
	v_pk_fma_f32 v[78:79], v[198:199], v[78:79], v[142:143]
	v_pk_fma_f32 v[76:77], v[196:197], v[76:77], v[140:141]
	v_pk_fma_f32 v[74:75], v[194:195], v[74:75], v[138:139]
	v_pk_fma_f32 v[72:73], v[192:193], v[72:73], v[136:137]
	v_add_u32_e32 v237, 0xa0000, v236
	global_load_dwordx4 v[136:139], v237, s[48:49] offset:512
	global_load_dwordx4 v[140:143], v237, s[48:49] offset:528
	ds_read_b32 v234, v209 offset:8896
	s_waitcnt lgkmcnt(0)
	v_pk_mul_f32 v[68:69], v[68:69], v[234:235] op_sel_hi:[1,0]
	v_pk_mul_f32 v[70:71], v[70:71], v[234:235] op_sel_hi:[1,0]
	v_pk_mul_f32 v[64:65], v[64:65], v[234:235] op_sel_hi:[1,0]
	v_pk_mul_f32 v[66:67], v[66:67], v[234:235] op_sel_hi:[1,0]
	v_pk_fma_f32 v[70:71], v[198:199], v[70:71], v[134:135]
	v_pk_fma_f32 v[68:69], v[196:197], v[68:69], v[132:133]
	v_pk_fma_f32 v[66:67], v[194:195], v[66:67], v[130:131]
	v_pk_fma_f32 v[64:65], v[192:193], v[64:65], v[128:129]
	v_add_u32_e32 v237, 0xb0000, v236
	global_load_dwordx4 v[128:131], v237, s[48:49] offset:512
	global_load_dwordx4 v[132:135], v237, s[48:49] offset:528
	ds_read_b32 v234, v209 offset:8192
	s_waitcnt lgkmcnt(0)
	v_pk_mul_f32 v[60:61], v[60:61], v[234:235] op_sel_hi:[1,0]
	v_pk_mul_f32 v[62:63], v[62:63], v[234:235] op_sel_hi:[1,0]
	v_pk_mul_f32 v[56:57], v[56:57], v[234:235] op_sel_hi:[1,0]
	v_pk_mul_f32 v[58:59], v[58:59], v[234:235] op_sel_hi:[1,0]
	s_waitcnt vmcnt(14)
	v_pk_fma_f32 v[62:63], v[228:229], v[62:63], v[186:187]
	v_pk_fma_f32 v[60:61], v[226:227], v[60:61], v[184:185]
	v_pk_fma_f32 v[58:59], v[232:233], v[58:59], v[190:191]
	v_pk_fma_f32 v[56:57], v[230:231], v[56:57], v[188:189]
	ds_read_b32 v234, v209 offset:8256
	s_waitcnt lgkmcnt(0)
	v_pk_mul_f32 v[52:53], v[52:53], v[234:235] op_sel_hi:[1,0]
	v_pk_mul_f32 v[54:55], v[54:55], v[234:235] op_sel_hi:[1,0]
	v_pk_mul_f32 v[48:49], v[48:49], v[234:235] op_sel_hi:[1,0]
	v_pk_mul_f32 v[50:51], v[50:51], v[234:235] op_sel_hi:[1,0]
	s_waitcnt vmcnt(12)
	v_pk_fma_f32 v[54:55], v[228:229], v[54:55], v[178:179]
	v_pk_fma_f32 v[52:53], v[226:227], v[52:53], v[176:177]
	v_pk_fma_f32 v[50:51], v[232:233], v[50:51], v[182:183]
	v_pk_fma_f32 v[48:49], v[230:231], v[48:49], v[180:181]
	ds_read_b32 v234, v209 offset:8320
	s_waitcnt lgkmcnt(0)
	v_pk_mul_f32 v[44:45], v[44:45], v[234:235] op_sel_hi:[1,0]
	v_pk_mul_f32 v[46:47], v[46:47], v[234:235] op_sel_hi:[1,0]
	v_pk_mul_f32 v[40:41], v[40:41], v[234:235] op_sel_hi:[1,0]
	v_pk_mul_f32 v[42:43], v[42:43], v[234:235] op_sel_hi:[1,0]
	s_waitcnt vmcnt(10)
	v_pk_fma_f32 v[46:47], v[228:229], v[46:47], v[170:171]
	v_pk_fma_f32 v[44:45], v[226:227], v[44:45], v[168:169]
	v_pk_fma_f32 v[42:43], v[232:233], v[42:43], v[174:175]
	v_pk_fma_f32 v[40:41], v[230:231], v[40:41], v[172:173]
	ds_read_b32 v234, v209 offset:8384
	s_waitcnt lgkmcnt(0)
	v_pk_mul_f32 v[36:37], v[36:37], v[234:235] op_sel_hi:[1,0]
	v_pk_mul_f32 v[38:39], v[38:39], v[234:235] op_sel_hi:[1,0]
	v_pk_mul_f32 v[32:33], v[32:33], v[234:235] op_sel_hi:[1,0]
	v_pk_mul_f32 v[34:35], v[34:35], v[234:235] op_sel_hi:[1,0]
	s_waitcnt vmcnt(8)
	v_pk_fma_f32 v[38:39], v[228:229], v[38:39], v[162:163]
	v_pk_fma_f32 v[36:37], v[226:227], v[36:37], v[160:161]
	v_pk_fma_f32 v[34:35], v[232:233], v[34:35], v[166:167]
	v_pk_fma_f32 v[32:33], v[230:231], v[32:33], v[164:165]
	ds_read_b32 v234, v209 offset:8704
	s_waitcnt lgkmcnt(0)
	v_pk_mul_f32 v[28:29], v[28:29], v[234:235] op_sel_hi:[1,0]
	v_pk_mul_f32 v[30:31], v[30:31], v[234:235] op_sel_hi:[1,0]
	v_pk_mul_f32 v[24:25], v[24:25], v[234:235] op_sel_hi:[1,0]
	v_pk_mul_f32 v[26:27], v[26:27], v[234:235] op_sel_hi:[1,0]
	s_waitcnt vmcnt(6)
	v_pk_fma_f32 v[30:31], v[228:229], v[30:31], v[154:155]
	v_pk_fma_f32 v[28:29], v[226:227], v[28:29], v[152:153]
	v_pk_fma_f32 v[26:27], v[232:233], v[26:27], v[158:159]
	v_pk_fma_f32 v[24:25], v[230:231], v[24:25], v[156:157]
	ds_read_b32 v234, v209 offset:8768
	s_waitcnt lgkmcnt(0)
	v_pk_mul_f32 v[20:21], v[20:21], v[234:235] op_sel_hi:[1,0]
	v_pk_mul_f32 v[22:23], v[22:23], v[234:235] op_sel_hi:[1,0]
	v_pk_mul_f32 v[16:17], v[16:17], v[234:235] op_sel_hi:[1,0]
	v_pk_mul_f32 v[18:19], v[18:19], v[234:235] op_sel_hi:[1,0]
	s_waitcnt vmcnt(4)
	v_pk_fma_f32 v[22:23], v[228:229], v[22:23], v[146:147]
	v_pk_fma_f32 v[20:21], v[226:227], v[20:21], v[144:145]
	v_pk_fma_f32 v[18:19], v[232:233], v[18:19], v[150:151]
	v_pk_fma_f32 v[16:17], v[230:231], v[16:17], v[148:149]
	ds_read_b32 v234, v209 offset:8832
	s_waitcnt lgkmcnt(0)
	v_pk_mul_f32 v[12:13], v[12:13], v[234:235] op_sel_hi:[1,0]
	v_pk_mul_f32 v[14:15], v[14:15], v[234:235] op_sel_hi:[1,0]
	v_pk_mul_f32 v[8:9], v[8:9], v[234:235] op_sel_hi:[1,0]
	v_pk_mul_f32 v[10:11], v[10:11], v[234:235] op_sel_hi:[1,0]
	s_waitcnt vmcnt(2)
	v_pk_fma_f32 v[14:15], v[228:229], v[14:15], v[138:139]
	v_pk_fma_f32 v[12:13], v[226:227], v[12:13], v[136:137]
	v_pk_fma_f32 v[10:11], v[232:233], v[10:11], v[142:143]
	v_pk_fma_f32 v[8:9], v[230:231], v[8:9], v[140:141]
	ds_read_b32 v234, v209 offset:8896
	s_waitcnt lgkmcnt(0)
	v_pk_mul_f32 v[4:5], v[4:5], v[234:235] op_sel_hi:[1,0]
	v_pk_mul_f32 v[6:7], v[6:7], v[234:235] op_sel_hi:[1,0]
	v_pk_mul_f32 v[0:1], v[0:1], v[234:235] op_sel_hi:[1,0]
	v_pk_mul_f32 v[2:3], v[2:3], v[234:235] op_sel_hi:[1,0]
	s_waitcnt vmcnt(0)
	v_pk_fma_f32 v[6:7], v[228:229], v[6:7], v[130:131]
	v_pk_fma_f32 v[4:5], v[226:227], v[4:5], v[128:129]
	v_pk_fma_f32 v[2:3], v[232:233], v[2:3], v[134:135]
	v_pk_fma_f32 v[0:1], v[230:231], v[0:1], v[132:133]
	v_mul_f32_e32 v164, v59, v59
	v_fmac_f32_e32 v164, v58, v58
	v_mul_f32_e32 v160, v113, v113
	v_mul_f32_e32 v161, v115, v115
	v_fmac_f32_e32 v160, v112, v112
	v_fmac_f32_e32 v161, v114, v114
	v_add_f32_e32 v160, v160, v161
	v_mul_f32_e32 v162, v117, v117
	v_mul_f32_e32 v163, v119, v119
	v_fmac_f32_e32 v162, v116, v116
	v_fmac_f32_e32 v163, v118, v118
	v_add_f32_e32 v161, v162, v163
	v_add_f32_e32 v160, v160, v161
	v_mul_f32_e32 v161, v61, v61
	v_mul_f32_e32 v162, v63, v63
	v_fmac_f32_e32 v161, v60, v60
	v_fmac_f32_e32 v162, v62, v62
	v_mul_f32_e32 v163, v57, v57
	v_add_f32_e32 v161, v161, v162
	v_fmac_f32_e32 v163, v56, v56
	v_add_f32_e32 v161, v160, v161
	v_add_f32_e32 v162, v163, v164
	v_add_f32_e32 v161, v162, v161
	v_mov_b32_e32 v162, v161
	s_nop 1
	v_permlane16_swap_b32_e32 v161, v162
	v_add_u32_e32 v144, s27, v210
	v_ashrrev_i32_e32 v145, 31, v144
	v_add_u32_e32 v150, 16, v144
	v_ashrrev_i32_e32 v151, 31, v150
	v_add_u32_e32 v148, 32, v144
	v_ashrrev_i32_e32 v149, 31, v148
	v_add_u32_e32 v146, 48, v144
	v_ashrrev_i32_e32 v147, 31, v146
	v_add_u32_e32 v142, 0x80, v144
	v_ashrrev_i32_e32 v143, 31, v142
	v_add_u32_e32 v140, 0x90, v144
	v_ashrrev_i32_e32 v141, 31, v140
	v_add_u32_e32 v138, 0xa0, v144
	v_ashrrev_i32_e32 v139, 31, v138
	v_add_u32_e32 v136, 0xb0, v144
	v_ashrrev_i32_e32 v137, 31, v136
	v_add_f32_e32 v128, v161, v162
	v_mov_b32_e32 v129, v128
	s_nop 1
	v_permlane32_swap_b32_e32 v128, v129
	s_and_saveexec_b64 s[16:17], s[8:9]
	s_lshl_b32 s20, s15, 10
	s_add_i32 s20, s25, s20
	v_lshl_add_u32 v130, v208, 4, s20
	v_add_f32_e32 v128, v128, v129
	ds_write_b32 v130, v128
	s_or_b64 exec, exec, s[16:17]
	v_mul_f32_e32 v128, v121, v121
	v_mul_f32_e32 v129, v123, v123
	v_fmac_f32_e32 v128, v120, v120
	v_fmac_f32_e32 v129, v122, v122
	v_add_f32_e32 v128, v128, v129
	v_mul_f32_e32 v129, v125, v125
	v_mul_f32_e32 v130, v127, v127
	v_fmac_f32_e32 v129, v124, v124
	v_fmac_f32_e32 v130, v126, v126
	v_add_f32_e32 v129, v129, v130
	v_add_f32_e32 v128, v128, v129
	v_mul_f32_e32 v129, v53, v53
	v_mul_f32_e32 v130, v55, v55
	v_fmac_f32_e32 v129, v52, v52
	v_fmac_f32_e32 v130, v54, v54
	v_add_f32_e32 v129, v129, v130
	v_add_f32_e32 v128, v128, v129
	v_mul_f32_e32 v129, v49, v49
	v_mul_f32_e32 v130, v51, v51
	v_fmac_f32_e32 v129, v48, v48
	v_fmac_f32_e32 v130, v50, v50
	v_add_f32_e32 v129, v129, v130
	v_add_f32_e32 v128, v129, v128
	v_mov_b32_e32 v129, v128
	s_nop 1
	v_permlane16_swap_b32_e32 v128, v129
	v_add_f32_e32 v128, v128, v129
	v_mov_b32_e32 v129, v128
	s_nop 1
	v_permlane32_swap_b32_e32 v128, v129
	s_and_saveexec_b64 s[16:17], s[8:9]
	s_lshl_b32 s20, s15, 10
	s_add_i32 s20, s25, s20
	v_lshl_add_u32 v130, v208, 4, s20
	v_add_f32_e32 v128, v128, v129
	ds_write_b32 v130, v128 offset:256
	s_or_b64 exec, exec, s[16:17]
	v_mul_f32_e32 v128, v105, v105
	v_mul_f32_e32 v129, v107, v107
	v_fmac_f32_e32 v128, v104, v104
	v_fmac_f32_e32 v129, v106, v106
	v_add_f32_e32 v128, v128, v129
	v_mul_f32_e32 v129, v109, v109
	v_mul_f32_e32 v130, v111, v111
	v_fmac_f32_e32 v129, v108, v108
	v_fmac_f32_e32 v130, v110, v110
	v_add_f32_e32 v129, v129, v130
	v_add_f32_e32 v128, v128, v129
	v_mul_f32_e32 v129, v45, v45
	v_mul_f32_e32 v130, v47, v47
	v_fmac_f32_e32 v129, v44, v44
	v_fmac_f32_e32 v130, v46, v46
	v_add_f32_e32 v129, v129, v130
	v_add_f32_e32 v128, v128, v129
	v_mul_f32_e32 v129, v41, v41
	v_mul_f32_e32 v130, v43, v43
	v_fmac_f32_e32 v129, v40, v40
	v_fmac_f32_e32 v130, v42, v42
	v_add_f32_e32 v129, v129, v130
	v_add_f32_e32 v128, v129, v128
	v_mov_b32_e32 v129, v128
	s_nop 1
	v_permlane16_swap_b32_e32 v128, v129
	v_add_f32_e32 v128, v128, v129
	v_mov_b32_e32 v129, v128
	s_nop 1
	v_permlane32_swap_b32_e32 v128, v129
	s_and_saveexec_b64 s[16:17], s[8:9]
	s_lshl_b32 s20, s15, 10
	s_add_i32 s20, s25, s20
	v_lshl_add_u32 v130, v208, 4, s20
	v_add_f32_e32 v128, v128, v129
	ds_write_b32 v130, v128 offset:512
	s_or_b64 exec, exec, s[16:17]
	v_mul_f32_e32 v128, v101, v101
	v_mul_f32_e32 v129, v103, v103
	v_fmac_f32_e32 v128, v100, v100
	v_fmac_f32_e32 v129, v102, v102
	v_add_f32_e32 v128, v128, v129
	v_mul_f32_e32 v129, v97, v97
	v_mul_f32_e32 v130, v99, v99
	v_fmac_f32_e32 v129, v96, v96
	v_fmac_f32_e32 v130, v98, v98
	v_add_f32_e32 v129, v129, v130
	v_add_f32_e32 v128, v128, v129
	v_mul_f32_e32 v129, v37, v37
	v_mul_f32_e32 v130, v39, v39
	v_fmac_f32_e32 v129, v36, v36
	v_fmac_f32_e32 v130, v38, v38
	v_add_f32_e32 v129, v129, v130
	v_add_f32_e32 v128, v128, v129
	v_mul_f32_e32 v129, v33, v33
	v_mul_f32_e32 v130, v35, v35
	v_fmac_f32_e32 v129, v32, v32
	v_fmac_f32_e32 v130, v34, v34
	v_add_f32_e32 v129, v129, v130
	v_add_f32_e32 v128, v129, v128
	v_mov_b32_e32 v129, v128
	s_nop 1
	v_permlane16_swap_b32_e32 v128, v129
	v_add_f32_e32 v128, v128, v129
	v_mov_b32_e32 v129, v128
	s_nop 1
	v_permlane32_swap_b32_e32 v128, v129
	s_and_saveexec_b64 s[16:17], s[8:9]
	s_lshl_b32 s20, s15, 10
	s_add_i32 s20, s25, s20
	v_lshl_add_u32 v130, v208, 4, s20
	v_add_f32_e32 v128, v128, v129
	ds_write_b32 v130, v128 offset:768
	s_or_b64 exec, exec, s[16:17]
	v_mul_f32_e32 v128, v93, v93
	v_mul_f32_e32 v129, v95, v95
	v_fmac_f32_e32 v128, v92, v92
	v_fmac_f32_e32 v129, v94, v94
	v_add_f32_e32 v128, v128, v129
	v_mul_f32_e32 v129, v89, v89
	v_mul_f32_e32 v130, v91, v91
	v_fmac_f32_e32 v129, v88, v88
	v_fmac_f32_e32 v130, v90, v90
	v_add_f32_e32 v129, v129, v130
	v_add_f32_e32 v128, v128, v129
	v_mul_f32_e32 v129, v29, v29
	v_mul_f32_e32 v130, v31, v31
	v_fmac_f32_e32 v129, v28, v28
	v_fmac_f32_e32 v130, v30, v30
	v_add_f32_e32 v129, v129, v130
	v_add_f32_e32 v128, v128, v129
	v_mul_f32_e32 v129, v25, v25
	v_mul_f32_e32 v130, v27, v27
	v_fmac_f32_e32 v129, v24, v24
	v_fmac_f32_e32 v130, v26, v26
	v_add_f32_e32 v129, v129, v130
	v_add_f32_e32 v128, v129, v128
	v_mov_b32_e32 v129, v128
	s_nop 1
	v_permlane16_swap_b32_e32 v128, v129
	v_add_f32_e32 v128, v128, v129
	v_mov_b32_e32 v129, v128
	s_nop 1
	v_permlane32_swap_b32_e32 v128, v129
	s_and_saveexec_b64 s[16:17], s[8:9]
	s_lshl_b32 s20, s15, 10
	s_add_i32 s20, s25, s20
	v_lshl_add_u32 v130, v208, 4, s20
	v_add_f32_e32 v128, v128, v129
	ds_write_b32 v130, v128 offset:2048
	s_or_b64 exec, exec, s[16:17]
	v_mul_f32_e32 v128, v85, v85
	v_mul_f32_e32 v129, v87, v87
	v_fmac_f32_e32 v128, v84, v84
	v_fmac_f32_e32 v129, v86, v86
	v_add_f32_e32 v128, v128, v129
	v_mul_f32_e32 v129, v81, v81
	v_mul_f32_e32 v130, v83, v83
	v_fmac_f32_e32 v129, v80, v80
	v_fmac_f32_e32 v130, v82, v82
	v_add_f32_e32 v129, v129, v130
	v_add_f32_e32 v128, v128, v129
	v_mul_f32_e32 v129, v21, v21
	v_mul_f32_e32 v130, v23, v23
	v_fmac_f32_e32 v129, v20, v20
	v_fmac_f32_e32 v130, v22, v22
	v_add_f32_e32 v129, v129, v130
	v_add_f32_e32 v128, v128, v129
	v_mul_f32_e32 v129, v17, v17
	v_mul_f32_e32 v130, v19, v19
	v_fmac_f32_e32 v129, v16, v16
	v_fmac_f32_e32 v130, v18, v18
	v_add_f32_e32 v129, v129, v130
	v_add_f32_e32 v128, v129, v128
	v_mov_b32_e32 v129, v128
	s_nop 1
	v_permlane16_swap_b32_e32 v128, v129
	v_add_f32_e32 v128, v128, v129
	v_mov_b32_e32 v129, v128
	s_nop 1
	v_permlane32_swap_b32_e32 v128, v129
	s_and_saveexec_b64 s[16:17], s[8:9]
	s_lshl_b32 s20, s15, 10
	s_add_i32 s20, s25, s20
	v_lshl_add_u32 v130, v208, 4, s20
	v_add_f32_e32 v128, v128, v129
	ds_write_b32 v130, v128 offset:2304
	s_or_b64 exec, exec, s[16:17]
	v_mul_f32_e32 v128, v77, v77
	v_mul_f32_e32 v129, v79, v79
	v_fmac_f32_e32 v128, v76, v76
	v_fmac_f32_e32 v129, v78, v78
	v_add_f32_e32 v128, v128, v129
	v_mul_f32_e32 v129, v73, v73
	v_mul_f32_e32 v130, v75, v75
	v_fmac_f32_e32 v129, v72, v72
	v_fmac_f32_e32 v130, v74, v74
	v_add_f32_e32 v129, v129, v130
	v_add_f32_e32 v128, v128, v129
	v_mul_f32_e32 v129, v13, v13
	v_mul_f32_e32 v130, v15, v15
	v_fmac_f32_e32 v129, v12, v12
	v_fmac_f32_e32 v130, v14, v14
	v_add_f32_e32 v129, v129, v130
	v_add_f32_e32 v128, v128, v129
	v_mul_f32_e32 v129, v9, v9
	v_mul_f32_e32 v130, v11, v11
	v_fmac_f32_e32 v129, v8, v8
	v_fmac_f32_e32 v130, v10, v10
	v_add_f32_e32 v129, v129, v130
	v_add_f32_e32 v128, v129, v128
	v_mov_b32_e32 v129, v128
	s_nop 1
	v_permlane16_swap_b32_e32 v128, v129
	v_add_f32_e32 v128, v128, v129
	v_mov_b32_e32 v129, v128
	s_nop 1
	v_permlane32_swap_b32_e32 v128, v129
	s_and_saveexec_b64 s[16:17], s[8:9]
	s_lshl_b32 s20, s15, 10
	s_add_i32 s20, s25, s20
	v_lshl_add_u32 v130, v208, 4, s20
	v_add_f32_e32 v128, v128, v129
	ds_write_b32 v130, v128 offset:2560
	s_or_b64 exec, exec, s[16:17]
	v_mul_f32_e32 v128, v69, v69
	v_mul_f32_e32 v129, v71, v71
	v_fmac_f32_e32 v128, v68, v68
	v_fmac_f32_e32 v129, v70, v70
	v_add_f32_e32 v128, v128, v129
	v_mul_f32_e32 v129, v65, v65
	v_mul_f32_e32 v130, v67, v67
	v_fmac_f32_e32 v129, v64, v64
	v_fmac_f32_e32 v130, v66, v66
	v_add_f32_e32 v129, v129, v130
	v_add_f32_e32 v128, v128, v129
	v_mul_f32_e32 v129, v5, v5
	v_mul_f32_e32 v130, v7, v7
	v_fmac_f32_e32 v129, v4, v4
	v_fmac_f32_e32 v130, v6, v6
	v_add_f32_e32 v129, v129, v130
	v_add_f32_e32 v128, v128, v129
	v_mul_f32_e32 v129, v1, v1
	v_mul_f32_e32 v130, v3, v3
	v_fmac_f32_e32 v129, v0, v0
	v_fmac_f32_e32 v130, v2, v2
	v_add_f32_e32 v129, v129, v130
	v_add_f32_e32 v128, v129, v128
	v_mov_b32_e32 v129, v128
	s_nop 1
	v_permlane16_swap_b32_e32 v128, v129
	v_add_f32_e32 v128, v128, v129
	v_mov_b32_e32 v129, v128
	s_nop 1
	v_permlane32_swap_b32_e32 v128, v129
	s_and_saveexec_b64 s[16:17], s[8:9]
	s_lshl_b32 s8, s15, 10
	s_add_i32 s25, s25, s8
	v_lshl_add_u32 v130, v208, 4, s25
	v_add_f32_e32 v128, v128, v129
	ds_write_b32 v130, v128 offset:2816
	s_or_b64 exec, exec, s[16:17]
	s_waitcnt lgkmcnt(0)
	s_barrier
	s_add_u32 s8, s18, 0x29b80000
	s_addc_u32 s9, s19, 0
	s_and_saveexec_b64 s[16:17], s[10:11]
	s_cbranch_execz .LBB0_737
	ds_read_b128 v[128:131], v212
	v_lshlrev_b64 v[132:133], 5, v[202:203]
	s_ashr_i32 s47, s46, 31
	s_waitcnt lgkmcnt(0)
	v_mov_b32_e32 v134, v129
	v_mov_b32_e32 v135, v130
	v_mov_b32_e32 v129, v131
	v_pk_add_f32 v[128:129], v[134:135], v[128:129]
	v_lshl_add_u64 v[130:131], s[8:9], 0, v[132:133]
	v_pk_add_f32 v[128:129], v[128:129], v[128:129] op_sel:[0,1] op_sel_hi:[1,0]
	v_lshl_add_u64 v[130:131], s[46:47], 3, v[130:131]
	v_mov_b32_e32 v129, 0
	global_store_dwordx2 v[130:131], v[128:129], off sc1
